# per-token expert lists no longer sorted (a 2 MB column slice is L2-resident, sweep order is irrelevant); lists staged through LDS once
# speedup vs baseline: 1.0198x; 1.0106x over previous
; DEV void peer_gather(const Params& P, int l, int m0, const int* idxs, const float* gs) {
;     ...
;   const int row = lane >> 4, rmap = ((row & 1) << 1) | (row >> 1);
;   u32x4 nxa = *(const u32x4*)(hn + (size_t)(m0 + wid * 16) * DM + lane * 16), nxb = *(const u32x4*)(hn + (size_t)(m0 + wid * 16) * DM + lane * 16 + 8);
;   int ni0 = idxs[(wid * 16) * 128 + lane], ni1 = idxs[(wid * 16) * 128 + 64 + lane];
;   float ng0 = gs[(wid * 16) * 128 + lane], ng1 = gs[(wid * 16) * 128 + 64 + lane];
;   sort_lists(lane, ni0, ni1, ng0, ng1);
.LBB0_313:
	s_waitcnt vmcnt(0) lgkmcnt(0)
	v_and_b32_e32 v233, 63, v176
	v_lshlrev_b32_e32 v234, 2, v233
	v_and_b32_e32 v116, 7, v233
	v_lshlrev_b32_e32 v235, 4, v116
	v_lshlrev_b32_e32 v236, 5, v116
	v_lshrrev_b32_e32 v117, 3, v233
	v_lshlrev_b32_e32 v237, 2, v117
	v_lshl_add_u32 v239, v116, 3, v117
	v_lshlrev_b32_e32 v239, 2, v239
	v_lshlrev_b32_e32 v238, 4, v116
	v_and_b32_e32 v117, 1, v117
	v_lshl_add_u32 v238, v117, 2, v238
	v_bfe_u32 v117, v233, 4, 1
	v_lshl_add_u32 v238, v117, 1, v238
	v_lshrrev_b32_e32 v117, 5, v233
	v_add_u32_e32 v238, v117, v238
	v_lshlrev_b32_e32 v238, 2, v238
	v_add_u32_e32 v249, 0, v237
	v_add_u32_e32 v250, 32, v237
	v_add_u32_e32 v251, 64, v237
	v_add_u32_e32 v252, 96, v237
	v_add_u32_e32 v253, 128, v237
	v_add_u32_e32 v254, 160, v237
	v_add_u32_e32 v255, 192, v237
	v_add_u32_e32 v153, 224, v237
	v_readfirstlane_b32 s33, v176
	s_lshr_b32 s33, s33, 6
	s_lshl_b32 s101, s33, 13
	s_lshl_b32 s33, s33, 4
	v_readlane_b32 s3, v231, 30
	s_add_u32 s3, s3, s33
	v_readlane_b32 s82, v231, 26
	v_readlane_b32 s83, v231, 27
	s_nop 4
	s_add_u32 s98, s33, 0
	s_lshl_b32 s98, s98, 9
	v_add_u32_e32 v116, s98, v234
	global_load_dword v0, v116, s[82:83]
	global_load_dword v1, v116, s[82:83] offset:256
	s_add_u32 s98, s33, 1
	s_lshl_b32 s98, s98, 9
	v_add_u32_e32 v117, s98, v234
	global_load_dword v2, v117, s[82:83]
	global_load_dword v3, v117, s[82:83] offset:256
	s_add_u32 s98, s33, 2
	s_lshl_b32 s98, s98, 9
	v_add_u32_e32 v118, s98, v234
	global_load_dword v4, v118, s[82:83]
	global_load_dword v5, v118, s[82:83] offset:256
	s_add_u32 s98, s33, 3
	s_lshl_b32 s98, s98, 9
	v_add_u32_e32 v119, s98, v234
	global_load_dword v6, v119, s[82:83]
	global_load_dword v7, v119, s[82:83] offset:256
	s_add_u32 s98, s33, 4
	s_lshl_b32 s98, s98, 9
	v_add_u32_e32 v116, s98, v234
	global_load_dword v8, v116, s[82:83]
	global_load_dword v9, v116, s[82:83] offset:256
	s_add_u32 s98, s33, 5
	s_lshl_b32 s98, s98, 9
	v_add_u32_e32 v117, s98, v234
	global_load_dword v10, v117, s[82:83]
	global_load_dword v11, v117, s[82:83] offset:256
	s_add_u32 s98, s33, 6
	s_lshl_b32 s98, s98, 9
	v_add_u32_e32 v118, s98, v234
	global_load_dword v12, v118, s[82:83]
	global_load_dword v13, v118, s[82:83] offset:256
	s_add_u32 s98, s33, 7
	s_lshl_b32 s98, s98, 9
	v_add_u32_e32 v119, s98, v234
	global_load_dword v14, v119, s[82:83]
	global_load_dword v15, v119, s[82:83] offset:256
	s_add_u32 s98, s33, 8
	s_lshl_b32 s98, s98, 9
	v_add_u32_e32 v116, s98, v234
	global_load_dword v16, v116, s[82:83]
	global_load_dword v17, v116, s[82:83] offset:256
	s_add_u32 s98, s33, 9
	s_lshl_b32 s98, s98, 9
	v_add_u32_e32 v117, s98, v234
	global_load_dword v18, v117, s[82:83]
	global_load_dword v19, v117, s[82:83] offset:256
	s_add_u32 s98, s33, 10
	s_lshl_b32 s98, s98, 9
	v_add_u32_e32 v118, s98, v234
	global_load_dword v20, v118, s[82:83]
	global_load_dword v21, v118, s[82:83] offset:256
	s_add_u32 s98, s33, 11
	s_lshl_b32 s98, s98, 9
	v_add_u32_e32 v119, s98, v234
	global_load_dword v22, v119, s[82:83]
	global_load_dword v23, v119, s[82:83] offset:256
	s_add_u32 s98, s33, 12
	s_lshl_b32 s98, s98, 9
	v_add_u32_e32 v116, s98, v234
	global_load_dword v24, v116, s[82:83]
	global_load_dword v25, v116, s[82:83] offset:256
	s_add_u32 s98, s33, 13
	s_lshl_b32 s98, s98, 9
	v_add_u32_e32 v117, s98, v234
	global_load_dword v26, v117, s[82:83]
	global_load_dword v27, v117, s[82:83] offset:256
	s_add_u32 s98, s33, 14
	s_lshl_b32 s98, s98, 9
	v_add_u32_e32 v118, s98, v234
	global_load_dword v28, v118, s[82:83]
	global_load_dword v29, v118, s[82:83] offset:256
	s_add_u32 s98, s33, 15
	s_lshl_b32 s98, s98, 9
	v_add_u32_e32 v119, s98, v234
	global_load_dword v30, v119, s[82:83]
	global_load_dword v31, v119, s[82:83] offset:256
	v_add_u32_e32 v144, s101, v234
	s_waitcnt vmcnt(30)
	ds_write_b32 v144, v0 offset:0
	ds_write_b32 v144, v1 offset:256
	s_waitcnt vmcnt(28)
	ds_write_b32 v144, v2 offset:512
	ds_write_b32 v144, v3 offset:768
	s_waitcnt vmcnt(26)
	ds_write_b32 v144, v4 offset:1024
	ds_write_b32 v144, v5 offset:1280
	s_waitcnt vmcnt(24)
	ds_write_b32 v144, v6 offset:1536
	ds_write_b32 v144, v7 offset:1792
	s_waitcnt vmcnt(22)
	ds_write_b32 v144, v8 offset:2048
	ds_write_b32 v144, v9 offset:2304
	s_waitcnt vmcnt(20)
	ds_write_b32 v144, v10 offset:2560
	ds_write_b32 v144, v11 offset:2816
	s_waitcnt vmcnt(18)
	ds_write_b32 v144, v12 offset:3072
	ds_write_b32 v144, v13 offset:3328
	s_waitcnt vmcnt(16)
	ds_write_b32 v144, v14 offset:3584
	ds_write_b32 v144, v15 offset:3840
	s_waitcnt vmcnt(14)
	ds_write_b32 v144, v16 offset:4096
	ds_write_b32 v144, v17 offset:4352
	s_waitcnt vmcnt(12)
	ds_write_b32 v144, v18 offset:4608
	ds_write_b32 v144, v19 offset:4864
	s_waitcnt vmcnt(10)
	ds_write_b32 v144, v20 offset:5120
	ds_write_b32 v144, v21 offset:5376
	s_waitcnt vmcnt(8)
	ds_write_b32 v144, v22 offset:5632
	ds_write_b32 v144, v23 offset:5888
	s_waitcnt vmcnt(6)
	ds_write_b32 v144, v24 offset:6144
	ds_write_b32 v144, v25 offset:6400
	s_waitcnt vmcnt(4)
	ds_write_b32 v144, v26 offset:6656
	ds_write_b32 v144, v27 offset:6912
	s_waitcnt vmcnt(2)
	ds_write_b32 v144, v28 offset:7168
	ds_write_b32 v144, v29 offset:7424
	s_waitcnt vmcnt(0)
	ds_write_b32 v144, v30 offset:7680
	ds_write_b32 v144, v31 offset:7936
	s_waitcnt lgkmcnt(0)
	s_mov_b32 s2, 0
; DEV void sort_lists(int lane, int& myi0, int& myi1, float& myg0, float& myg1) {
; #pragma unroll
;     for (int k = 2; k <= 128; k <<= 1) {
; #pragma unroll
;       for (int j = k >> 1; j >= 1; j >>= 1) {
;         if (j == 64) {
;           const bool sw_ = myi1 < myi0;
;           const int ti = sw_ ? myi1 : myi0, tj = sw_ ? myi0 : myi1; const float tg = sw_ ? myg1 : myg0, th = sw_ ? myg0 : myg1;
;           myi0 = ti; myi1 = tj; myg0 = tg; myg1 = th;
;         } else {
;           const bool lower = (lane & j) == 0;
;           {
;             const bool up = (k == 128) ? true : ((k == 64) ? true : ((lane & k) == 0));
;             const int oi = __shfl_xor(myi0, j); const float og = __shfl_xor(myg0, j);
;             const bool take = (lower == up) ? (oi < myi0) : (oi > myi0);
;             myi0 = take ? oi : myi0; myg0 = take ? og : myg0;
;           }
;           {
;             const bool up = (k == 128) ? true : ((k == 64) ? false : ((lane & k) == 0));
;             const int oi = __shfl_xor(myi1, j); const float og = __shfl_xor(myg1, j);
;             const bool take = (lower == up) ? (oi < myi1) : (oi > myi1);
;             myi1 = take ? oi : myi1; myg1 = take ? og : myg1;
;           }
;         }
;       }
;     }
; }
; DEV void peer_gather(const Params& P, int l, int m0, const int* idxs, const float* gs) {
;     ...
;   int ni0 = idxs[(wid * 16) * 128 + lane], ni1 = idxs[(wid * 16) * 128 + 64 + lane];
;   float ng0 = gs[(wid * 16) * 128 + lane], ng1 = gs[(wid * 16) * 128 + 64 + lane];
;   sort_lists(lane, ni0, ni1, ng0, ng1);
.Lpg0_p0:
	s_lshl_b32 s98, s2, 11
	s_add_u32 s98, s98, s101
	v_add_u32_e32 v116, s98, v234
	ds_read_b32 v241, v116 offset:0
	ds_read_b32 v242, v116 offset:256
	ds_read_b32 v243, v116 offset:512
	ds_read_b32 v244, v116 offset:768
	ds_read_b32 v245, v116 offset:1024
	ds_read_b32 v246, v116 offset:1280
	ds_read_b32 v247, v116 offset:1536
	ds_read_b32 v248, v116 offset:1792
	s_waitcnt lgkmcnt(0)
	v_or_b32_e32 v116, 64, v233
	v_lshl_or_b32 v241, v241, 7, v233
	v_lshl_or_b32 v242, v242, 7, v116
	v_lshl_or_b32 v243, v243, 7, v233
	v_lshl_or_b32 v244, v244, 7, v116
	v_lshl_or_b32 v245, v245, 7, v233
	v_lshl_or_b32 v246, v246, 7, v116
	v_lshl_or_b32 v247, v247, 7, v233
	v_lshl_or_b32 v248, v248, 7, v116
	v_mov_b32_e32 v117, 0
	s_lshl_b32 s98, s2, 11
	s_add_u32 s98, s98, s101
	v_add_u32_e32 v116, s98, v234
	v_lshl_add_u32 v119, v235, 2, v237
	v_add_u32_e32 v119, s98, v119
	ds_write_b32 v119, v241 offset:0
	ds_write_b32 v119, v242 offset:32
	ds_write_b32 v119, v243 offset:512
	ds_write_b32 v119, v244 offset:544
	ds_write_b32 v119, v245 offset:1024
	ds_write_b32 v119, v246 offset:1056
	ds_write_b32 v119, v247 offset:1536
	ds_write_b32 v119, v248 offset:1568
	v_add_u32_e32 v118, 0x10000, v116
	ds_write_b32 v118, v117 offset:0
	ds_write_b32 v118, v117 offset:256
	ds_write_b32 v118, v117 offset:512
	ds_write_b32 v118, v117 offset:768
	ds_write_b32 v118, v117 offset:1024
	ds_write_b32 v118, v117 offset:1280
	ds_write_b32 v118, v117 offset:1536
	ds_write_b32 v118, v117 offset:1792
	s_add_u32 s2, s2, 1
	s_cmp_lt_u32 s2, 4
	s_cbranch_scc1 .Lpg0_p0
	s_waitcnt lgkmcnt(0)
	v_readfirstlane_b32 s82, v128
	v_readfirstlane_b32 s83, v129
	s_nop 4
	v_readfirstlane_b32 s80, v124
	v_readfirstlane_b32 s81, v125
	s_nop 4
	s_mov_b32 s2, 0xffffff80
	s_mov_b32 s86, 0xcccccccc
	s_mov_b32 s87, 0xcccccccc
	s_mov_b32 s88, 0xaaaaaaaa
	s_mov_b32 s89, 0xaaaaaaaa
	s_mov_b32 s90, 0xf0f0f0f0
	s_mov_b32 s91, 0xf0f0f0f0
	s_lshl_b32 vcc_lo, s3, 11
	s_add_u32 s82, s82, vcc_lo
	s_addc_u32 s83, s83, 0
	v_lshl_add_u32 v246, v237, 4, s101
	v_lshrrev_b32_e32 v247, 2, v235
	v_add_u32_e32 v247, v247, v246
	v_add_u32_e32 v247, 0x10000, v247
	s_mov_b32 s100, 0
	s_mov_b32 s98, 0
	s_mov_b32 s99, 0
	s_lshl3_add_u32 vcc_lo, s98, s99
	v_lshl_add_u32 v119, vcc_lo, 8, v236
	global_load_dwordx4 v[80:83], v119, s[82:83]
	global_load_dwordx4 v[84:87], v119, s[82:83] offset:16
	v_lshl_add_u32 v116, s98, 9, v246
	ds_read_b128 v[112:115], v116
	ds_read_b128 v[138:141], v116 offset:16
	ds_read_b128 v[250:253], v116 offset:32
	ds_read_b128 v[242:245], v116 offset:48
	v_lshl_or_b32 v240, s99, 21, v235
	s_waitcnt lgkmcnt(0)
	v_and_or_b32 v112, v112, s2, v240
	v_and_or_b32 v113, v113, s2, v240
	global_load_dwordx4 v[0:3], v112, s[80:81]
	global_load_dwordx4 v[4:7], v113, s[80:81]
	v_and_or_b32 v114, v114, s2, v240
	v_and_or_b32 v115, v115, s2, v240
	global_load_dwordx4 v[8:11], v114, s[80:81]
	global_load_dwordx4 v[12:15], v115, s[80:81]
	v_and_or_b32 v138, v138, s2, v240
	v_and_or_b32 v139, v139, s2, v240
	global_load_dwordx4 v[16:19], v138, s[80:81]
	global_load_dwordx4 v[20:23], v139, s[80:81]
	v_and_or_b32 v140, v140, s2, v240
	v_and_or_b32 v141, v141, s2, v240
	global_load_dwordx4 v[24:27], v140, s[80:81]
	global_load_dwordx4 v[28:31], v141, s[80:81]
	v_and_or_b32 v250, v250, s2, v240
	v_and_or_b32 v251, v251, s2, v240
	global_load_dwordx4 v[32:35], v250, s[80:81]
	global_load_dwordx4 v[36:39], v251, s[80:81]
	v_and_or_b32 v252, v252, s2, v240
	v_and_or_b32 v253, v253, s2, v240
	global_load_dwordx4 v[40:43], v252, s[80:81]
	global_load_dwordx4 v[44:47], v253, s[80:81]
	v_and_or_b32 v242, v242, s2, v240
	v_and_or_b32 v243, v243, s2, v240
	global_load_dwordx4 v[48:51], v242, s[80:81]
	global_load_dwordx4 v[52:55], v243, s[80:81]
	v_and_or_b32 v244, v244, s2, v240
	v_and_or_b32 v245, v245, s2, v240
	global_load_dwordx4 v[56:59], v244, s[80:81]
	global_load_dwordx4 v[60:63], v245, s[80:81]
	s_mov_b32 s92, 1
	v_lshl_add_u32 v116, s92, 9, v246
	ds_read_b128 v[112:115], v116
	ds_read_b128 v[138:141], v116 offset:16
	ds_read_b128 v[250:253], v116 offset:32
	ds_read_b128 v[242:245], v116 offset:48

; DEV void peer_gather(const Params& P, int l, int m0, const int* idxs, const float* gs) {
;     ...
;   const int row = lane >> 4, rmap = ((row & 1) << 1) | (row >> 1);
;   u32x4 nxa = *(const u32x4*)(hn + (size_t)(m0 + wid * 16) * DM + lane * 16), nxb = *(const u32x4*)(hn + (size_t)(m0 + wid * 16) * DM + lane * 16 + 8);
;   int ni0 = idxs[(wid * 16) * 128 + lane], ni1 = idxs[(wid * 16) * 128 + 64 + lane];
;   float ng0 = gs[(wid * 16) * 128 + lane], ng1 = gs[(wid * 16) * 128 + 64 + lane];
;   sort_lists(lane, ni0, ni1, ng0, ng1);
.LBB0_752:
	s_waitcnt vmcnt(0) lgkmcnt(0)
	v_and_b32_e32 v233, 63, v176
	v_lshlrev_b32_e32 v234, 2, v233
	v_and_b32_e32 v116, 7, v233
	v_lshlrev_b32_e32 v235, 4, v116
	v_lshlrev_b32_e32 v236, 5, v116
	v_lshrrev_b32_e32 v117, 3, v233
	v_lshlrev_b32_e32 v237, 2, v117
	v_lshl_add_u32 v239, v116, 3, v117
	v_lshlrev_b32_e32 v239, 2, v239
	v_lshlrev_b32_e32 v238, 4, v116
	v_and_b32_e32 v117, 1, v117
	v_lshl_add_u32 v238, v117, 2, v238
	v_bfe_u32 v117, v233, 4, 1
	v_lshl_add_u32 v238, v117, 1, v238
	v_lshrrev_b32_e32 v117, 5, v233
	v_add_u32_e32 v238, v117, v238
	v_lshlrev_b32_e32 v238, 2, v238
	v_add_u32_e32 v249, 0, v237
	v_add_u32_e32 v250, 32, v237
	v_add_u32_e32 v251, 64, v237
	v_add_u32_e32 v252, 96, v237
	v_add_u32_e32 v253, 128, v237
	v_add_u32_e32 v254, 160, v237
	v_add_u32_e32 v255, 192, v237
	v_add_u32_e32 v153, 224, v237
	v_readfirstlane_b32 s33, v176
	s_lshr_b32 s33, s33, 6
	s_lshl_b32 s101, s33, 13
	s_lshl_b32 s33, s33, 4
	v_readlane_b32 s3, v231, 15
	s_add_u32 s3, s3, s33
	v_readlane_b32 s82, v231, 13
	v_readlane_b32 s83, v231, 14
	s_nop 4
	s_add_u32 s98, s33, 0
	s_lshl_b32 s98, s98, 9
	v_add_u32_e32 v116, s98, v234
	global_load_dword v0, v116, s[82:83]
	global_load_dword v1, v116, s[82:83] offset:256
	s_add_u32 s98, s33, 1
	s_lshl_b32 s98, s98, 9
	v_add_u32_e32 v117, s98, v234
	global_load_dword v2, v117, s[82:83]
	global_load_dword v3, v117, s[82:83] offset:256
	s_add_u32 s98, s33, 2
	s_lshl_b32 s98, s98, 9
	v_add_u32_e32 v118, s98, v234
	global_load_dword v4, v118, s[82:83]
	global_load_dword v5, v118, s[82:83] offset:256
	s_add_u32 s98, s33, 3
	s_lshl_b32 s98, s98, 9
	v_add_u32_e32 v119, s98, v234
	global_load_dword v6, v119, s[82:83]
	global_load_dword v7, v119, s[82:83] offset:256
	s_add_u32 s98, s33, 4
	s_lshl_b32 s98, s98, 9
	v_add_u32_e32 v116, s98, v234
	global_load_dword v8, v116, s[82:83]
	global_load_dword v9, v116, s[82:83] offset:256
	s_add_u32 s98, s33, 5
	s_lshl_b32 s98, s98, 9
	v_add_u32_e32 v117, s98, v234
	global_load_dword v10, v117, s[82:83]
	global_load_dword v11, v117, s[82:83] offset:256
	s_add_u32 s98, s33, 6
	s_lshl_b32 s98, s98, 9
	v_add_u32_e32 v118, s98, v234
	global_load_dword v12, v118, s[82:83]
	global_load_dword v13, v118, s[82:83] offset:256
	s_add_u32 s98, s33, 7
	s_lshl_b32 s98, s98, 9
	v_add_u32_e32 v119, s98, v234
	global_load_dword v14, v119, s[82:83]
	global_load_dword v15, v119, s[82:83] offset:256
	s_add_u32 s98, s33, 8
	s_lshl_b32 s98, s98, 9
	v_add_u32_e32 v116, s98, v234
	global_load_dword v16, v116, s[82:83]
	global_load_dword v17, v116, s[82:83] offset:256
	s_add_u32 s98, s33, 9
	s_lshl_b32 s98, s98, 9
	v_add_u32_e32 v117, s98, v234
	global_load_dword v18, v117, s[82:83]
	global_load_dword v19, v117, s[82:83] offset:256
	s_add_u32 s98, s33, 10
	s_lshl_b32 s98, s98, 9
	v_add_u32_e32 v118, s98, v234
	global_load_dword v20, v118, s[82:83]
	global_load_dword v21, v118, s[82:83] offset:256
	s_add_u32 s98, s33, 11
	s_lshl_b32 s98, s98, 9
	v_add_u32_e32 v119, s98, v234
	global_load_dword v22, v119, s[82:83]
	global_load_dword v23, v119, s[82:83] offset:256
	s_add_u32 s98, s33, 12
	s_lshl_b32 s98, s98, 9
	v_add_u32_e32 v116, s98, v234
	global_load_dword v24, v116, s[82:83]
	global_load_dword v25, v116, s[82:83] offset:256
	s_add_u32 s98, s33, 13
	s_lshl_b32 s98, s98, 9
	v_add_u32_e32 v117, s98, v234
	global_load_dword v26, v117, s[82:83]
	global_load_dword v27, v117, s[82:83] offset:256
	s_add_u32 s98, s33, 14
	s_lshl_b32 s98, s98, 9
	v_add_u32_e32 v118, s98, v234
	global_load_dword v28, v118, s[82:83]
	global_load_dword v29, v118, s[82:83] offset:256
	s_add_u32 s98, s33, 15
	s_lshl_b32 s98, s98, 9
	v_add_u32_e32 v119, s98, v234
	global_load_dword v30, v119, s[82:83]
	global_load_dword v31, v119, s[82:83] offset:256
	v_add_u32_e32 v144, s101, v234
	s_waitcnt vmcnt(30)
	ds_write_b32 v144, v0 offset:0
	ds_write_b32 v144, v1 offset:256
	s_waitcnt vmcnt(28)
	ds_write_b32 v144, v2 offset:512
	ds_write_b32 v144, v3 offset:768
	s_waitcnt vmcnt(26)
	ds_write_b32 v144, v4 offset:1024
	ds_write_b32 v144, v5 offset:1280
	s_waitcnt vmcnt(24)
	ds_write_b32 v144, v6 offset:1536
	ds_write_b32 v144, v7 offset:1792
	s_waitcnt vmcnt(22)
	ds_write_b32 v144, v8 offset:2048
	ds_write_b32 v144, v9 offset:2304
	s_waitcnt vmcnt(20)
	ds_write_b32 v144, v10 offset:2560
	ds_write_b32 v144, v11 offset:2816
	s_waitcnt vmcnt(18)
	ds_write_b32 v144, v12 offset:3072
	ds_write_b32 v144, v13 offset:3328
	s_waitcnt vmcnt(16)
	ds_write_b32 v144, v14 offset:3584
	ds_write_b32 v144, v15 offset:3840
	s_waitcnt vmcnt(14)
	ds_write_b32 v144, v16 offset:4096
	ds_write_b32 v144, v17 offset:4352
	s_waitcnt vmcnt(12)
	ds_write_b32 v144, v18 offset:4608
	ds_write_b32 v144, v19 offset:4864
	s_waitcnt vmcnt(10)
	ds_write_b32 v144, v20 offset:5120
	ds_write_b32 v144, v21 offset:5376
	s_waitcnt vmcnt(8)
	ds_write_b32 v144, v22 offset:5632
	ds_write_b32 v144, v23 offset:5888
	s_waitcnt vmcnt(6)
	ds_write_b32 v144, v24 offset:6144
	ds_write_b32 v144, v25 offset:6400
	s_waitcnt vmcnt(4)
	ds_write_b32 v144, v26 offset:6656
	ds_write_b32 v144, v27 offset:6912
	s_waitcnt vmcnt(2)
	ds_write_b32 v144, v28 offset:7168
	ds_write_b32 v144, v29 offset:7424
	s_waitcnt vmcnt(0)
	ds_write_b32 v144, v30 offset:7680
	ds_write_b32 v144, v31 offset:7936
	s_waitcnt lgkmcnt(0)
	s_mov_b32 s2, 0
; DEV void sort_lists(int lane, int& myi0, int& myi1, float& myg0, float& myg1) {
; #pragma unroll
;     for (int k = 2; k <= 128; k <<= 1) {
; #pragma unroll
;       for (int j = k >> 1; j >= 1; j >>= 1) {
;         if (j == 64) {
;           const bool sw_ = myi1 < myi0;
;           const int ti = sw_ ? myi1 : myi0, tj = sw_ ? myi0 : myi1; const float tg = sw_ ? myg1 : myg0, th = sw_ ? myg0 : myg1;
;           myi0 = ti; myi1 = tj; myg0 = tg; myg1 = th;
;         } else {
;           const bool lower = (lane & j) == 0;
;           {
;             const bool up = (k == 128) ? true : ((k == 64) ? true : ((lane & k) == 0));
;             const int oi = __shfl_xor(myi0, j); const float og = __shfl_xor(myg0, j);
;             const bool take = (lower == up) ? (oi < myi0) : (oi > myi0);
;             myi0 = take ? oi : myi0; myg0 = take ? og : myg0;
;           }
;           {
;             const bool up = (k == 128) ? true : ((k == 64) ? false : ((lane & k) == 0));
;             const int oi = __shfl_xor(myi1, j); const float og = __shfl_xor(myg1, j);
;             const bool take = (lower == up) ? (oi < myi1) : (oi > myi1);
;             myi1 = take ? oi : myi1; myg1 = take ? og : myg1;
;           }
;         }
;       }
;     }
; }
; DEV void peer_gather(const Params& P, int l, int m0, const int* idxs, const float* gs) {
;     ...
;   int ni0 = idxs[(wid * 16) * 128 + lane], ni1 = idxs[(wid * 16) * 128 + 64 + lane];
;   float ng0 = gs[(wid * 16) * 128 + lane], ng1 = gs[(wid * 16) * 128 + 64 + lane];
;   sort_lists(lane, ni0, ni1, ng0, ng1);
.Lpg1_p0:
	s_lshl_b32 s98, s2, 11
	s_add_u32 s98, s98, s101
	v_add_u32_e32 v116, s98, v234
	ds_read_b32 v241, v116 offset:0
	ds_read_b32 v242, v116 offset:256
	ds_read_b32 v243, v116 offset:512
	ds_read_b32 v244, v116 offset:768
	ds_read_b32 v245, v116 offset:1024
	ds_read_b32 v246, v116 offset:1280
	ds_read_b32 v247, v116 offset:1536
	ds_read_b32 v248, v116 offset:1792
	s_waitcnt lgkmcnt(0)
	v_or_b32_e32 v116, 64, v233
	v_lshl_or_b32 v241, v241, 7, v233
	v_lshl_or_b32 v242, v242, 7, v116
	v_lshl_or_b32 v243, v243, 7, v233
	v_lshl_or_b32 v244, v244, 7, v116
	v_lshl_or_b32 v245, v245, 7, v233
	v_lshl_or_b32 v246, v246, 7, v116
	v_lshl_or_b32 v247, v247, 7, v233
	v_lshl_or_b32 v248, v248, 7, v116
	v_mov_b32_e32 v117, 0
	s_lshl_b32 s98, s2, 11
	s_add_u32 s98, s98, s101
	v_add_u32_e32 v116, s98, v234
	v_lshl_add_u32 v119, v235, 2, v237
	v_add_u32_e32 v119, s98, v119
	ds_write_b32 v119, v241 offset:0
	ds_write_b32 v119, v242 offset:32
	ds_write_b32 v119, v243 offset:512
	ds_write_b32 v119, v244 offset:544
	ds_write_b32 v119, v245 offset:1024
	ds_write_b32 v119, v246 offset:1056
	ds_write_b32 v119, v247 offset:1536
	ds_write_b32 v119, v248 offset:1568
	v_add_u32_e32 v118, 0x10000, v116
	ds_write_b32 v118, v117 offset:0
	ds_write_b32 v118, v117 offset:256
	ds_write_b32 v118, v117 offset:512
	ds_write_b32 v118, v117 offset:768
	ds_write_b32 v118, v117 offset:1024
	ds_write_b32 v118, v117 offset:1280
	ds_write_b32 v118, v117 offset:1536
	ds_write_b32 v118, v117 offset:1792
	s_add_u32 s2, s2, 1
	s_cmp_lt_u32 s2, 4
	s_cbranch_scc1 .Lpg1_p0
	s_waitcnt lgkmcnt(0)
	v_readfirstlane_b32 s82, v122
	v_readfirstlane_b32 s83, v123
	s_nop 4
	v_readfirstlane_b32 s80, v126
	v_readfirstlane_b32 s81, v127
	s_nop 4
	s_mov_b32 s2, 0xffffff80
	s_mov_b32 s86, 0xcccccccc
	s_mov_b32 s87, 0xcccccccc
	s_mov_b32 s88, 0xaaaaaaaa
	s_mov_b32 s89, 0xaaaaaaaa
	s_mov_b32 s90, 0xf0f0f0f0
	s_mov_b32 s91, 0xf0f0f0f0
	s_lshl_b32 vcc_lo, s3, 11
	s_add_u32 s82, s82, vcc_lo
	s_addc_u32 s83, s83, 0
	v_lshl_add_u32 v246, v237, 4, s101
	v_lshrrev_b32_e32 v247, 2, v235
	v_add_u32_e32 v247, v247, v246
	v_add_u32_e32 v247, 0x10000, v247
	s_mov_b32 s100, 0
	s_mov_b32 s98, 0
	s_mov_b32 s99, 0
	s_lshl3_add_u32 vcc_lo, s98, s99
	v_lshl_add_u32 v119, vcc_lo, 8, v236
	global_load_dwordx4 v[80:83], v119, s[82:83]
	global_load_dwordx4 v[84:87], v119, s[82:83] offset:16
	v_lshl_add_u32 v116, s98, 9, v246
	ds_read_b128 v[112:115], v116
	ds_read_b128 v[138:141], v116 offset:16
	ds_read_b128 v[250:253], v116 offset:32
	ds_read_b128 v[242:245], v116 offset:48
	v_lshl_or_b32 v240, s99, 21, v235
	s_waitcnt lgkmcnt(0)
	v_and_or_b32 v112, v112, s2, v240
	v_and_or_b32 v113, v113, s2, v240
	global_load_dwordx4 v[0:3], v112, s[80:81]
	global_load_dwordx4 v[4:7], v113, s[80:81]
	v_and_or_b32 v114, v114, s2, v240
	v_and_or_b32 v115, v115, s2, v240
	global_load_dwordx4 v[8:11], v114, s[80:81]
	global_load_dwordx4 v[12:15], v115, s[80:81]
	v_and_or_b32 v138, v138, s2, v240
	v_and_or_b32 v139, v139, s2, v240
	global_load_dwordx4 v[16:19], v138, s[80:81]
	global_load_dwordx4 v[20:23], v139, s[80:81]
	v_and_or_b32 v140, v140, s2, v240
	v_and_or_b32 v141, v141, s2, v240
	global_load_dwordx4 v[24:27], v140, s[80:81]
	global_load_dwordx4 v[28:31], v141, s[80:81]
	v_and_or_b32 v250, v250, s2, v240
	v_and_or_b32 v251, v251, s2, v240
	global_load_dwordx4 v[32:35], v250, s[80:81]
	global_load_dwordx4 v[36:39], v251, s[80:81]
	v_and_or_b32 v252, v252, s2, v240
	v_and_or_b32 v253, v253, s2, v240
	global_load_dwordx4 v[40:43], v252, s[80:81]
	global_load_dwordx4 v[44:47], v253, s[80:81]
	v_and_or_b32 v242, v242, s2, v240
	v_and_or_b32 v243, v243, s2, v240
	global_load_dwordx4 v[48:51], v242, s[80:81]
	global_load_dwordx4 v[52:55], v243, s[80:81]
	v_and_or_b32 v244, v244, s2, v240
	v_and_or_b32 v245, v245, s2, v240
	global_load_dwordx4 v[56:59], v244, s[80:81]
	global_load_dwordx4 v[60:63], v245, s[80:81]
	s_mov_b32 s92, 1
	v_lshl_add_u32 v116, s92, 9, v246
	ds_read_b128 v[112:115], v116
	ds_read_b128 v[138:141], v116 offset:16
	ds_read_b128 v[250:253], v116 offset:32
	ds_read_b128 v[242:245], v116 offset:48
